# v113 + G6 final output rows stored write-through (sc1) instead of nt
# baseline (speedup 1.0000x reference)
.LBB0_1388:
	ds_read_b128 v[128:131], v173
	ds_read_b128 v[132:135], v173 offset:1024
	ds_read_b128 v[136:139], v173 offset:2048
	ds_read_b128 v[140:143], v173 offset:3072
	ds_read_b128 v[144:147], v174
	ds_read_b128 v[148:151], v174 offset:1024
	ds_read_b128 v[152:155], v174 offset:2048
	ds_read_b128 v[156:159], v174 offset:3072
	s_add_u32 s10, s8, 0x100
	s_addc_u32 s11, s9, 0
	s_cmp_eq_u32 s42, 40
	s_cselect_b32 s15, s7, s11
	s_cselect_b32 s14, s6, s10
	s_cselect_b32 s13, s1, s41
	s_cselect_b32 s12, s0, s40
	v_lshl_add_u64 v[208:209], s[8:9], 0, v[168:169]
	s_add_i32 m0, s22, 0xc000
	ds_read_b128 v[176:179], v175
	ds_read_b128 v[180:183], v175 offset:1024
	ds_read_b128 v[184:187], v175 offset:2048
	ds_read_b128 v[188:191], v175 offset:3072
	ds_read_b128 v[192:195], v175 offset:4096
	ds_read_b128 v[196:199], v175 offset:5120
	ds_read_b128 v[200:203], v175 offset:6144
	ds_read_b128 v[204:207], v175 offset:7168
	global_load_lds_dwordx4 v[208:209], off
	v_lshl_add_u64 v[208:209], s[8:9], 0, v[170:171]
	s_add_i32 m0, s22, 0xe000
	s_nop 0
	global_load_lds_dwordx4 v[208:209], off
	s_waitcnt vmcnt(8)
	s_waitcnt lgkmcnt(0)
	s_barrier
	s_setprio 1
	s_waitcnt lgkmcnt(0)
	v_mfma_f32_16x16x32_bf16 v[124:127], v[128:131], v[176:179], v[124:127]
	v_mfma_f32_16x16x32_bf16 v[120:123], v[136:139], v[176:179], v[120:123]
	v_mfma_f32_16x16x32_bf16 v[116:119], v[128:131], v[184:187], v[116:119]
	v_mfma_f32_16x16x32_bf16 v[112:115], v[136:139], v[184:187], v[112:115]
	v_mfma_f32_16x16x32_bf16 v[96:99], v[128:131], v[192:195], v[96:99]
	v_mfma_f32_16x16x32_bf16 v[88:91], v[136:139], v[192:195], v[88:91]
	v_mfma_f32_16x16x32_bf16 v[80:83], v[128:131], v[200:203], v[80:83]
	v_mfma_f32_16x16x32_bf16 v[72:75], v[136:139], v[200:203], v[72:75]
	v_mfma_f32_16x16x32_bf16 v[124:127], v[132:135], v[180:183], v[124:127]
	v_mfma_f32_16x16x32_bf16 v[120:123], v[140:143], v[180:183], v[120:123]
	v_mfma_f32_16x16x32_bf16 v[116:119], v[132:135], v[188:191], v[116:119]
	v_mfma_f32_16x16x32_bf16 v[112:115], v[140:143], v[188:191], v[112:115]
	v_mfma_f32_16x16x32_bf16 v[96:99], v[132:135], v[196:199], v[96:99]
	v_mfma_f32_16x16x32_bf16 v[88:91], v[140:143], v[196:199], v[88:91]
	v_mfma_f32_16x16x32_bf16 v[80:83], v[132:135], v[204:207], v[80:83]
	v_mfma_f32_16x16x32_bf16 v[72:75], v[140:143], v[204:207], v[72:75]
	s_setprio 0
	s_setprio 1
	v_mfma_f32_16x16x32_bf16 v[108:111], v[144:147], v[176:179], v[108:111]
	v_mfma_f32_16x16x32_bf16 v[104:107], v[152:155], v[176:179], v[104:107]
	v_mfma_f32_16x16x32_bf16 v[100:103], v[144:147], v[184:187], v[100:103]
	v_mfma_f32_16x16x32_bf16 v[92:95], v[152:155], v[184:187], v[92:95]
	v_mfma_f32_16x16x32_bf16 v[84:87], v[144:147], v[192:195], v[84:87]
	v_mfma_f32_16x16x32_bf16 v[76:79], v[152:155], v[192:195], v[76:79]
	v_mfma_f32_16x16x32_bf16 v[68:71], v[144:147], v[200:203], v[68:71]
	v_mfma_f32_16x16x32_bf16 v[64:67], v[152:155], v[200:203], v[64:67]
	v_mfma_f32_16x16x32_bf16 v[108:111], v[148:151], v[180:183], v[108:111]
	v_mfma_f32_16x16x32_bf16 v[104:107], v[156:159], v[180:183], v[104:107]
	v_mfma_f32_16x16x32_bf16 v[100:103], v[148:151], v[188:191], v[100:103]
	v_mfma_f32_16x16x32_bf16 v[92:95], v[156:159], v[188:191], v[92:95]
	v_mfma_f32_16x16x32_bf16 v[84:87], v[148:151], v[196:199], v[84:87]
	v_mfma_f32_16x16x32_bf16 v[76:79], v[156:159], v[196:199], v[76:79]
	v_mfma_f32_16x16x32_bf16 v[68:71], v[148:151], v[204:207], v[68:71]
	v_mfma_f32_16x16x32_bf16 v[64:67], v[156:159], v[204:207], v[64:67]
	s_setprio 0
	s_barrier
	s_add_i32 s8, s31, s17
	v_lshl_add_u64 v[208:209], s[12:13], 0, v[164:165]
	s_mov_b32 m0, s8
	ds_read_b128 v[176:179], v175 offset:16384
	ds_read_b128 v[180:183], v175 offset:17408
	ds_read_b128 v[184:187], v175 offset:18432
	ds_read_b128 v[188:191], v175 offset:19456
	ds_read_b128 v[192:195], v175 offset:20480
	ds_read_b128 v[196:199], v175 offset:21504
	ds_read_b128 v[200:203], v175 offset:22528
	ds_read_b128 v[204:207], v175 offset:23552
	global_load_lds_dwordx4 v[208:209], off
	s_add_i32 m0, s8, 0x2000
	s_add_u32 s8, s12, 0xb0000
	v_lshl_add_u64 v[210:211], s[12:13], 0, v[160:161]
	s_addc_u32 s9, s13, 0
	s_add_i32 s43, s34, s17
	global_load_lds_dwordx4 v[210:211], off
	v_lshl_add_u64 v[212:213], s[8:9], 0, v[164:165]
	s_mov_b32 m0, s43
	v_lshl_add_u64 v[214:215], s[14:15], 0, v[162:163]
	global_load_lds_dwordx4 v[212:213], off
	v_lshl_add_u64 v[212:213], s[8:9], 0, v[160:161]
	s_add_i32 m0, s43, 0x2000
	s_nop 0
	global_load_lds_dwordx4 v[212:213], off
	v_lshl_add_u64 v[212:213], s[14:15], 0, v[166:167]
	s_mov_b32 m0, s22
	s_nop 0
	global_load_lds_dwordx4 v[212:213], off
	s_mov_b32 m0, s23
	s_nop 0
	global_load_lds_dwordx4 v[214:215], off
	s_waitcnt vmcnt(8)
	s_waitcnt lgkmcnt(0)
	s_barrier
	s_setprio 1
	s_waitcnt lgkmcnt(0)
	v_mfma_f32_16x16x32_bf16 v[60:63], v[128:131], v[176:179], v[60:63]
	v_mfma_f32_16x16x32_bf16 v[56:59], v[136:139], v[176:179], v[56:59]
	v_mfma_f32_16x16x32_bf16 v[48:51], v[128:131], v[184:187], v[48:51]
	v_mfma_f32_16x16x32_bf16 v[40:43], v[136:139], v[184:187], v[40:43]
	v_mfma_f32_16x16x32_bf16 v[32:35], v[128:131], v[192:195], v[32:35]
	v_mfma_f32_16x16x32_bf16 v[24:27], v[136:139], v[192:195], v[24:27]
	v_mfma_f32_16x16x32_bf16 v[16:19], v[128:131], v[200:203], v[16:19]
	v_mfma_f32_16x16x32_bf16 v[8:11], v[136:139], v[200:203], v[8:11]
	v_mfma_f32_16x16x32_bf16 v[60:63], v[132:135], v[180:183], v[60:63]
	v_mfma_f32_16x16x32_bf16 v[56:59], v[140:143], v[180:183], v[56:59]
	v_mfma_f32_16x16x32_bf16 v[48:51], v[132:135], v[188:191], v[48:51]
	v_mfma_f32_16x16x32_bf16 v[40:43], v[140:143], v[188:191], v[40:43]
	v_mfma_f32_16x16x32_bf16 v[32:35], v[132:135], v[196:199], v[32:35]
	v_mfma_f32_16x16x32_bf16 v[24:27], v[140:143], v[196:199], v[24:27]
	v_mfma_f32_16x16x32_bf16 v[16:19], v[132:135], v[204:207], v[16:19]
	v_mfma_f32_16x16x32_bf16 v[8:11], v[140:143], v[204:207], v[8:11]
	s_setprio 0
	s_setprio 1
	v_mfma_f32_16x16x32_bf16 v[52:55], v[144:147], v[176:179], v[52:55]
	v_mfma_f32_16x16x32_bf16 v[44:47], v[152:155], v[176:179], v[44:47]
	v_mfma_f32_16x16x32_bf16 v[36:39], v[144:147], v[184:187], v[36:39]
	v_mfma_f32_16x16x32_bf16 v[28:31], v[152:155], v[184:187], v[28:31]
	v_mfma_f32_16x16x32_bf16 v[20:23], v[144:147], v[192:195], v[20:23]
	v_mfma_f32_16x16x32_bf16 v[12:15], v[152:155], v[192:195], v[12:15]
	v_mfma_f32_16x16x32_bf16 v[4:7], v[144:147], v[200:203], v[4:7]
	v_mfma_f32_16x16x32_bf16 v[0:3], v[152:155], v[200:203], v[0:3]
	v_mfma_f32_16x16x32_bf16 v[52:55], v[148:151], v[180:183], v[52:55]
	v_mfma_f32_16x16x32_bf16 v[44:47], v[156:159], v[180:183], v[44:47]
	v_mfma_f32_16x16x32_bf16 v[36:39], v[148:151], v[188:191], v[36:39]
	v_mfma_f32_16x16x32_bf16 v[28:31], v[156:159], v[188:191], v[28:31]
	v_mfma_f32_16x16x32_bf16 v[20:23], v[148:151], v[196:199], v[20:23]
	v_mfma_f32_16x16x32_bf16 v[12:15], v[156:159], v[196:199], v[12:15]
	v_mfma_f32_16x16x32_bf16 v[4:7], v[148:151], v[204:207], v[4:7]
	v_mfma_f32_16x16x32_bf16 v[0:3], v[156:159], v[204:207], v[0:3]
	s_setprio 0
	s_barrier
	s_add_i32 s43, 0, 0x18000
	s_add_i32 s44, 0, 0x1c000
	v_add_u32_e32 v140, s43, v172
	v_add_u32_e32 v156, s44, v172
	ds_read_b128 v[128:131], v140
	ds_read_b128 v[132:135], v140 offset:1024
	ds_read_b128 v[136:139], v140 offset:2048
	ds_read_b128 v[140:143], v140 offset:3072
	ds_read_b128 v[144:147], v156
	ds_read_b128 v[148:151], v156 offset:1024
	ds_read_b128 v[152:155], v156 offset:2048
	ds_read_b128 v[156:159], v156 offset:3072
	s_add_u32 s8, s14, 0xb0000
	s_addc_u32 s9, s15, 0
	s_mov_b32 m0, s24
	v_lshl_add_u64 v[216:217], s[8:9], 0, v[166:167]
	ds_read_b128 v[176:179], v175 offset:32768
	ds_read_b128 v[180:183], v175 offset:33792
	ds_read_b128 v[184:187], v175 offset:34816
	ds_read_b128 v[188:191], v175 offset:35840
	ds_read_b128 v[192:195], v175 offset:36864
	ds_read_b128 v[196:199], v175 offset:37888
	ds_read_b128 v[200:203], v175 offset:38912
	ds_read_b128 v[204:207], v175 offset:39936
	global_load_lds_dwordx4 v[216:217], off
	v_lshl_add_u64 v[216:217], s[8:9], 0, v[162:163]
	s_mov_b32 m0, s25
	s_nop 0
	global_load_lds_dwordx4 v[216:217], off
	s_waitcnt vmcnt(8)
	s_waitcnt lgkmcnt(0)
	s_barrier
	s_setprio 1
	s_waitcnt lgkmcnt(0)
	v_mfma_f32_16x16x32_bf16 v[124:127], v[128:131], v[176:179], v[124:127]
	v_mfma_f32_16x16x32_bf16 v[120:123], v[136:139], v[176:179], v[120:123]
	v_mfma_f32_16x16x32_bf16 v[116:119], v[128:131], v[184:187], v[116:119]
	v_mfma_f32_16x16x32_bf16 v[112:115], v[136:139], v[184:187], v[112:115]
	v_mfma_f32_16x16x32_bf16 v[96:99], v[128:131], v[192:195], v[96:99]
	v_mfma_f32_16x16x32_bf16 v[88:91], v[136:139], v[192:195], v[88:91]
	v_mfma_f32_16x16x32_bf16 v[80:83], v[128:131], v[200:203], v[80:83]
	v_mfma_f32_16x16x32_bf16 v[72:75], v[136:139], v[200:203], v[72:75]
	v_mfma_f32_16x16x32_bf16 v[124:127], v[132:135], v[180:183], v[124:127]
	v_mfma_f32_16x16x32_bf16 v[120:123], v[140:143], v[180:183], v[120:123]
	v_mfma_f32_16x16x32_bf16 v[116:119], v[132:135], v[188:191], v[116:119]
	v_mfma_f32_16x16x32_bf16 v[112:115], v[140:143], v[188:191], v[112:115]
	v_mfma_f32_16x16x32_bf16 v[96:99], v[132:135], v[196:199], v[96:99]
	v_mfma_f32_16x16x32_bf16 v[88:91], v[140:143], v[196:199], v[88:91]
	v_mfma_f32_16x16x32_bf16 v[80:83], v[132:135], v[204:207], v[80:83]
	v_mfma_f32_16x16x32_bf16 v[72:75], v[140:143], v[204:207], v[72:75]
	s_setprio 0
	s_setprio 1
	v_mfma_f32_16x16x32_bf16 v[108:111], v[144:147], v[176:179], v[108:111]
	v_mfma_f32_16x16x32_bf16 v[104:107], v[152:155], v[176:179], v[104:107]
	v_mfma_f32_16x16x32_bf16 v[100:103], v[144:147], v[184:187], v[100:103]
	v_mfma_f32_16x16x32_bf16 v[92:95], v[152:155], v[184:187], v[92:95]
	v_mfma_f32_16x16x32_bf16 v[84:87], v[144:147], v[192:195], v[84:87]
	v_mfma_f32_16x16x32_bf16 v[76:79], v[152:155], v[192:195], v[76:79]
	v_mfma_f32_16x16x32_bf16 v[68:71], v[144:147], v[200:203], v[68:71]
	v_mfma_f32_16x16x32_bf16 v[64:67], v[152:155], v[200:203], v[64:67]
	v_mfma_f32_16x16x32_bf16 v[108:111], v[148:151], v[180:183], v[108:111]
	v_mfma_f32_16x16x32_bf16 v[104:107], v[156:159], v[180:183], v[104:107]
	v_mfma_f32_16x16x32_bf16 v[100:103], v[148:151], v[188:191], v[100:103]
	v_mfma_f32_16x16x32_bf16 v[92:95], v[156:159], v[188:191], v[92:95]
	v_mfma_f32_16x16x32_bf16 v[84:87], v[148:151], v[196:199], v[84:87]
	v_mfma_f32_16x16x32_bf16 v[76:79], v[156:159], v[196:199], v[76:79]
	v_mfma_f32_16x16x32_bf16 v[68:71], v[148:151], v[204:207], v[68:71]
	v_mfma_f32_16x16x32_bf16 v[64:67], v[156:159], v[204:207], v[64:67]
	s_setprio 0
	s_barrier
	s_add_i32 s8, s43, s17
	v_lshl_add_u64 v[208:209], v[208:209], 0, s[2:3]
	s_mov_b32 m0, s8
	ds_read_b128 v[176:179], v175 offset:49152
	ds_read_b128 v[180:183], v175 offset:50176
	ds_read_b128 v[184:187], v175 offset:51200
	ds_read_b128 v[188:191], v175 offset:52224
	ds_read_b128 v[192:195], v175 offset:53248
	ds_read_b128 v[196:199], v175 offset:54272
	ds_read_b128 v[200:203], v175 offset:55296
	ds_read_b128 v[204:207], v175 offset:56320
	global_load_lds_dwordx4 v[208:209], off
	s_add_i32 m0, s8, 0x2000
	s_add_u32 s8, s12, 0xb0080
	v_lshl_add_u64 v[208:209], v[210:211], 0, s[2:3]
	s_addc_u32 s9, s13, 0
	s_add_i32 s12, s44, s17
	global_load_lds_dwordx4 v[208:209], off
	v_lshl_add_u64 v[208:209], s[8:9], 0, v[164:165]
	s_mov_b32 m0, s12
	s_nop 0
	global_load_lds_dwordx4 v[208:209], off
	v_lshl_add_u64 v[208:209], s[8:9], 0, v[160:161]
	s_add_i32 m0, s12, 0x2000
	s_nop 0
	global_load_lds_dwordx4 v[208:209], off
	v_lshl_add_u64 v[208:209], v[212:213], 0, s[2:3]
	s_mov_b32 m0, s29
	s_nop 0
	global_load_lds_dwordx4 v[208:209], off
	v_lshl_add_u64 v[208:209], v[214:215], 0, s[2:3]
	s_mov_b32 m0, s30
	s_nop 0
	global_load_lds_dwordx4 v[208:209], off
	s_waitcnt vmcnt(8)
	s_waitcnt lgkmcnt(0)
	s_barrier
	s_setprio 1
	s_waitcnt lgkmcnt(0)
	v_mfma_f32_16x16x32_bf16 v[60:63], v[128:131], v[176:179], v[60:63]
	v_mfma_f32_16x16x32_bf16 v[56:59], v[136:139], v[176:179], v[56:59]
	v_mfma_f32_16x16x32_bf16 v[48:51], v[128:131], v[184:187], v[48:51]
	v_mfma_f32_16x16x32_bf16 v[40:43], v[136:139], v[184:187], v[40:43]
	v_mfma_f32_16x16x32_bf16 v[32:35], v[128:131], v[192:195], v[32:35]
	v_mfma_f32_16x16x32_bf16 v[24:27], v[136:139], v[192:195], v[24:27]
	v_mfma_f32_16x16x32_bf16 v[16:19], v[128:131], v[200:203], v[16:19]
	v_mfma_f32_16x16x32_bf16 v[8:11], v[136:139], v[200:203], v[8:11]
	v_mfma_f32_16x16x32_bf16 v[60:63], v[132:135], v[180:183], v[60:63]
	v_mfma_f32_16x16x32_bf16 v[56:59], v[140:143], v[180:183], v[56:59]
	v_mfma_f32_16x16x32_bf16 v[48:51], v[132:135], v[188:191], v[48:51]
	v_mfma_f32_16x16x32_bf16 v[40:43], v[140:143], v[188:191], v[40:43]
	v_mfma_f32_16x16x32_bf16 v[32:35], v[132:135], v[196:199], v[32:35]
	v_mfma_f32_16x16x32_bf16 v[24:27], v[140:143], v[196:199], v[24:27]
	v_mfma_f32_16x16x32_bf16 v[16:19], v[132:135], v[204:207], v[16:19]
	v_mfma_f32_16x16x32_bf16 v[8:11], v[140:143], v[204:207], v[8:11]
	s_setprio 0
	s_setprio 1
	v_mfma_f32_16x16x32_bf16 v[52:55], v[144:147], v[176:179], v[52:55]
	v_mfma_f32_16x16x32_bf16 v[44:47], v[152:155], v[176:179], v[44:47]
	v_mfma_f32_16x16x32_bf16 v[36:39], v[144:147], v[184:187], v[36:39]
	v_mfma_f32_16x16x32_bf16 v[28:31], v[152:155], v[184:187], v[28:31]
	v_mfma_f32_16x16x32_bf16 v[20:23], v[144:147], v[192:195], v[20:23]
	v_mfma_f32_16x16x32_bf16 v[12:15], v[152:155], v[192:195], v[12:15]
	v_mfma_f32_16x16x32_bf16 v[4:7], v[144:147], v[200:203], v[4:7]
	v_mfma_f32_16x16x32_bf16 v[0:3], v[152:155], v[200:203], v[0:3]
	v_mfma_f32_16x16x32_bf16 v[52:55], v[148:151], v[180:183], v[52:55]
	v_mfma_f32_16x16x32_bf16 v[44:47], v[156:159], v[180:183], v[44:47]
	v_mfma_f32_16x16x32_bf16 v[36:39], v[148:151], v[188:191], v[36:39]
	v_mfma_f32_16x16x32_bf16 v[28:31], v[156:159], v[188:191], v[28:31]
	v_mfma_f32_16x16x32_bf16 v[20:23], v[148:151], v[196:199], v[20:23]
	v_mfma_f32_16x16x32_bf16 v[12:15], v[156:159], v[196:199], v[12:15]
	v_mfma_f32_16x16x32_bf16 v[4:7], v[148:151], v[204:207], v[4:7]
	v_mfma_f32_16x16x32_bf16 v[0:3], v[156:159], v[204:207], v[0:3]
	s_setprio 0
	s_barrier
	s_add_i32 s42, s42, 2
	s_add_u32 s40, s40, 0x100
	s_addc_u32 s41, s41, 0
	s_cmp_gt_u32 s42, 41
	s_mov_b64 s[8:9], s[10:11]
	s_cbranch_scc0 .LBB0_1388
	s_lshl_b32 s8, s39, 8
	v_mbcnt_lo_u32_b32 v128, -1, 0
	v_mbcnt_hi_u32_b32 v128, -1, v128
	s_add_i32 s8, s8, s27
	v_and_or_b32 v129, v128, 15, s8
	s_lshl_b32 s8, s38, 8
	v_ashrrev_i32_e32 v128, 1, v128
	v_lshlrev_b32_e32 v129, 10, v129
	s_or_b32 s8, s8, s28
	v_and_b32_e32 v128, -8, v128
	v_add3_u32 v128, s8, v128, v129
	v_lshlrev_b32_e32 v177, 1, v128
	global_load_dwordx4 v[178:181], v177, s[48:49]
	v_add_u32_e32 v129, 0x100, v177
	global_load_dwordx4 v[182:185], v129, s[48:49]
	v_add_u32_e32 v129, 0x8000, v177
	v_add_u32_e32 v210, 0x10000, v177
	global_load_dwordx4 v[186:189], v129, s[48:49]
	global_load_dwordx4 v[194:197], v210, s[48:49]
	v_add_u32_e32 v129, 0x8100, v177
	global_load_dwordx4 v[190:193], v129, s[48:49]
	v_lshlrev_b32_e32 v176, 2, v128
	v_add_u32_e32 v128, 0x10100, v177
	v_add_u32_e32 v129, 0x18000, v177
	v_add_u32_e32 v130, 0x18100, v177
	v_add_u32_e32 v131, 0x40000, v177
	v_add_u32_e32 v132, 0x40100, v177
	v_add_u32_e32 v133, 0x48000, v177
	v_add_u32_e32 v134, 0x48100, v177
	v_add_u32_e32 v135, 0x50000, v177
	v_add_u32_e32 v136, 0x50100, v177
	v_add_u32_e32 v211, 0x58000, v177
	v_add_u32_e32 v212, 0x58100, v177
	global_load_dwordx4 v[198:201], v128, s[48:49]
	global_load_dwordx4 v[202:205], v129, s[48:49]
	global_load_dwordx4 v[206:209], v130, s[48:49]
	global_load_dwordx4 v[156:159], v131, s[48:49]
	global_load_dwordx4 v[152:155], v132, s[48:49]
	global_load_dwordx4 v[148:151], v133, s[48:49]
	global_load_dwordx4 v[144:147], v134, s[48:49]
	global_load_dwordx4 v[140:143], v135, s[48:49]
	s_nop 0
	global_load_dwordx4 v[136:139], v136, s[48:49]
	s_nop 0
	global_load_dwordx4 v[132:135], v211, s[48:49]
	global_load_dwordx4 v[128:131], v212, s[48:49]
	v_add_u32_e32 v177, v210, v177
	v_add_u32_e32 v216, 0x200, v176
	s_cmp_eq_u32 s26, s16
	s_mov_b32 s38, s36
	s_mov_b32 s39, s35
	s_mov_b64 s[10:11], s[0:1]
	s_mov_b64 s[8:9], s[6:7]
	s_waitcnt vmcnt(0)
	v_lshlrev_b32_e32 v210, 16, v178
	v_and_b32_e32 v211, 0xffff0000, v178
	v_lshlrev_b32_e32 v178, 16, v179
	v_and_b32_e32 v179, 0xffff0000, v179
	v_lshlrev_b32_e32 v212, 16, v180
	v_and_b32_e32 v213, 0xffff0000, v180
	v_lshlrev_b32_e32 v180, 16, v181
	v_and_b32_e32 v181, 0xffff0000, v181
	v_pk_add_f32 v[126:127], v[126:127], v[178:179]
	v_pk_add_f32 v[122:123], v[122:123], v[180:181]
	v_lshlrev_b32_e32 v178, 16, v182
	v_and_b32_e32 v179, 0xffff0000, v182
	v_lshlrev_b32_e32 v180, 16, v183
	v_and_b32_e32 v181, 0xffff0000, v183
	v_lshlrev_b32_e32 v182, 16, v184
	v_and_b32_e32 v183, 0xffff0000, v184
	v_pk_add_f32 v[124:125], v[124:125], v[210:211]
	v_pk_add_f32 v[120:121], v[120:121], v[212:213]
	v_lshlrev_b32_e32 v184, 16, v185
	v_and_b32_e32 v185, 0xffff0000, v185
	v_lshlrev_b32_e32 v210, 16, v186
	v_and_b32_e32 v211, 0xffff0000, v186
	v_lshlrev_b32_e32 v186, 16, v187
	v_and_b32_e32 v187, 0xffff0000, v187
	v_lshlrev_b32_e32 v212, 16, v188
	v_and_b32_e32 v213, 0xffff0000, v188
	v_lshlrev_b32_e32 v188, 16, v189
	v_and_b32_e32 v189, 0xffff0000, v189
	v_pk_add_f32 v[110:111], v[110:111], v[180:181]
	v_pk_add_f32 v[108:109], v[108:109], v[178:179]
	v_pk_add_f32 v[104:105], v[104:105], v[182:183]
	global_store_dwordx4 v176, v[124:127], s[4:5] sc1
	global_store_dwordx4 v176, v[120:123], s[4:5] offset:16 sc1
	v_pk_add_f32 v[106:107], v[106:107], v[184:185]
	v_pk_add_f32 v[118:119], v[118:119], v[186:187]
	v_pk_add_f32 v[116:117], v[116:117], v[210:211]
	v_pk_add_f32 v[114:115], v[114:115], v[188:189]
	v_pk_add_f32 v[112:113], v[112:113], v[212:213]
	global_store_dwordx4 v216, v[108:111], s[4:5] sc1
	global_store_dwordx4 v216, v[104:107], s[4:5] offset:16 sc1
	global_store_dwordx4 v177, v[116:119], s[4:5] sc1
	global_store_dwordx4 v177, v[112:115], s[4:5] offset:16 sc1
	v_lshlrev_b32_e32 v104, 16, v191
	v_and_b32_e32 v105, 0xffff0000, v191
	v_lshlrev_b32_e32 v214, 16, v190
	v_and_b32_e32 v215, 0xffff0000, v190
	v_pk_add_f32 v[102:103], v[102:103], v[104:105]
	v_lshlrev_b32_e32 v104, 16, v192
	v_and_b32_e32 v105, 0xffff0000, v192
	v_pk_add_f32 v[100:101], v[100:101], v[214:215]
	v_lshlrev_b32_e32 v106, 16, v193
	v_and_b32_e32 v107, 0xffff0000, v193
	v_pk_add_f32 v[92:93], v[92:93], v[104:105]
	v_add_u32_e32 v104, 0x10200, v176
	v_pk_add_f32 v[94:95], v[94:95], v[106:107]
	global_store_dwordx4 v104, v[100:103], s[4:5] sc1
	global_store_dwordx4 v104, v[92:95], s[4:5] offset:16 sc1
	s_nop 1
	v_lshlrev_b32_e32 v92, 16, v194
	v_and_b32_e32 v93, 0xffff0000, v194
	v_lshlrev_b32_e32 v94, 16, v195
	v_and_b32_e32 v95, 0xffff0000, v195
	v_pk_add_f32 v[92:93], v[96:97], v[92:93]
	v_lshlrev_b32_e32 v96, 16, v196
	v_and_b32_e32 v97, 0xffff0000, v196
	v_pk_add_f32 v[94:95], v[98:99], v[94:95]
	v_lshlrev_b32_e32 v98, 16, v197
	v_and_b32_e32 v99, 0xffff0000, v197
	v_pk_add_f32 v[88:89], v[88:89], v[96:97]
	v_add_u32_e32 v96, 0x20000, v176
	v_pk_add_f32 v[90:91], v[90:91], v[98:99]
	global_store_dwordx4 v96, v[92:95], s[4:5] sc1
	global_store_dwordx4 v96, v[88:91], s[4:5] offset:16 sc1
	s_nop 1
	v_lshlrev_b32_e32 v88, 16, v198
	v_and_b32_e32 v89, 0xffff0000, v198
	v_lshlrev_b32_e32 v90, 16, v199
	v_and_b32_e32 v91, 0xffff0000, v199
	v_pk_add_f32 v[84:85], v[84:85], v[88:89]
	v_lshlrev_b32_e32 v88, 16, v200
	v_and_b32_e32 v89, 0xffff0000, v200
	v_pk_add_f32 v[86:87], v[86:87], v[90:91]
	v_lshlrev_b32_e32 v90, 16, v201
	v_and_b32_e32 v91, 0xffff0000, v201
	v_pk_add_f32 v[76:77], v[76:77], v[88:89]
	v_add_u32_e32 v88, 0x20200, v176
	v_pk_add_f32 v[78:79], v[78:79], v[90:91]
	global_store_dwordx4 v88, v[84:87], s[4:5] sc1
	global_store_dwordx4 v88, v[76:79], s[4:5] offset:16 sc1
	s_nop 1
	v_lshlrev_b32_e32 v76, 16, v202
	v_and_b32_e32 v77, 0xffff0000, v202
	v_lshlrev_b32_e32 v78, 16, v203
	v_and_b32_e32 v79, 0xffff0000, v203
	v_pk_add_f32 v[76:77], v[80:81], v[76:77]
	v_lshlrev_b32_e32 v80, 16, v204
	v_and_b32_e32 v81, 0xffff0000, v204
	v_pk_add_f32 v[78:79], v[82:83], v[78:79]
	v_lshlrev_b32_e32 v82, 16, v205
	v_and_b32_e32 v83, 0xffff0000, v205
	v_pk_add_f32 v[72:73], v[72:73], v[80:81]
	v_add_u32_e32 v80, 0x30000, v176
	v_pk_add_f32 v[74:75], v[74:75], v[82:83]
	global_store_dwordx4 v80, v[76:79], s[4:5] sc1
	global_store_dwordx4 v80, v[72:75], s[4:5] offset:16 sc1
	s_nop 1
	v_lshlrev_b32_e32 v72, 16, v206
	v_and_b32_e32 v73, 0xffff0000, v206
	v_lshlrev_b32_e32 v74, 16, v207
	v_and_b32_e32 v75, 0xffff0000, v207
	v_pk_add_f32 v[68:69], v[68:69], v[72:73]
	v_lshlrev_b32_e32 v72, 16, v208
	v_and_b32_e32 v73, 0xffff0000, v208
	v_pk_add_f32 v[70:71], v[70:71], v[74:75]
	v_lshlrev_b32_e32 v74, 16, v209
	v_and_b32_e32 v75, 0xffff0000, v209
	v_pk_add_f32 v[64:65], v[64:65], v[72:73]
	v_add_u32_e32 v72, 0x30200, v176
	v_pk_add_f32 v[66:67], v[66:67], v[74:75]
	global_store_dwordx4 v72, v[68:71], s[4:5] sc1
	global_store_dwordx4 v72, v[64:67], s[4:5] offset:16 sc1
	s_nop 1
	v_lshlrev_b32_e32 v64, 16, v156
	v_and_b32_e32 v65, 0xffff0000, v156
	v_lshlrev_b32_e32 v66, 16, v157
	v_and_b32_e32 v67, 0xffff0000, v157
	v_pk_add_f32 v[60:61], v[60:61], v[64:65]
	v_lshlrev_b32_e32 v64, 16, v158
	v_and_b32_e32 v65, 0xffff0000, v158
	v_pk_add_f32 v[62:63], v[62:63], v[66:67]
	v_lshlrev_b32_e32 v66, 16, v159
	v_and_b32_e32 v67, 0xffff0000, v159
	v_pk_add_f32 v[56:57], v[56:57], v[64:65]
	v_add_u32_e32 v64, 0x80000, v176
	v_pk_add_f32 v[58:59], v[58:59], v[66:67]
	global_store_dwordx4 v64, v[60:63], s[4:5] sc1
	global_store_dwordx4 v64, v[56:59], s[4:5] offset:16 sc1
	s_nop 1
	v_lshlrev_b32_e32 v56, 16, v152
	v_and_b32_e32 v57, 0xffff0000, v152
	v_lshlrev_b32_e32 v58, 16, v153
	v_and_b32_e32 v59, 0xffff0000, v153
	v_pk_add_f32 v[52:53], v[52:53], v[56:57]
	v_lshlrev_b32_e32 v56, 16, v154
	v_and_b32_e32 v57, 0xffff0000, v154
	v_pk_add_f32 v[54:55], v[54:55], v[58:59]
	v_lshlrev_b32_e32 v58, 16, v155
	v_and_b32_e32 v59, 0xffff0000, v155
	v_pk_add_f32 v[44:45], v[44:45], v[56:57]
	v_add_u32_e32 v56, 0x80200, v176
	v_pk_add_f32 v[46:47], v[46:47], v[58:59]
	global_store_dwordx4 v56, v[52:55], s[4:5] sc1
	global_store_dwordx4 v56, v[44:47], s[4:5] offset:16 sc1
	s_nop 1
	v_lshlrev_b32_e32 v44, 16, v148
	v_and_b32_e32 v45, 0xffff0000, v148
	v_lshlrev_b32_e32 v46, 16, v149
	v_and_b32_e32 v47, 0xffff0000, v149
	v_pk_add_f32 v[44:45], v[48:49], v[44:45]
	v_lshlrev_b32_e32 v48, 16, v150
	v_and_b32_e32 v49, 0xffff0000, v150
	v_pk_add_f32 v[46:47], v[50:51], v[46:47]
	v_lshlrev_b32_e32 v50, 16, v151
	v_and_b32_e32 v51, 0xffff0000, v151
	v_pk_add_f32 v[40:41], v[40:41], v[48:49]
	v_add_u32_e32 v48, 0x90000, v176
	v_pk_add_f32 v[42:43], v[42:43], v[50:51]
	global_store_dwordx4 v48, v[44:47], s[4:5] sc1
	global_store_dwordx4 v48, v[40:43], s[4:5] offset:16 sc1
	s_nop 1
	v_lshlrev_b32_e32 v40, 16, v144
	v_and_b32_e32 v41, 0xffff0000, v144
	v_lshlrev_b32_e32 v42, 16, v145
	v_and_b32_e32 v43, 0xffff0000, v145
	v_pk_add_f32 v[36:37], v[36:37], v[40:41]
	v_lshlrev_b32_e32 v40, 16, v146
	v_and_b32_e32 v41, 0xffff0000, v146
	v_pk_add_f32 v[38:39], v[38:39], v[42:43]
	v_lshlrev_b32_e32 v42, 16, v147
	v_and_b32_e32 v43, 0xffff0000, v147
	v_pk_add_f32 v[28:29], v[28:29], v[40:41]
	v_add_u32_e32 v40, 0x90200, v176
	v_pk_add_f32 v[30:31], v[30:31], v[42:43]
	global_store_dwordx4 v40, v[36:39], s[4:5] sc1
	global_store_dwordx4 v40, v[28:31], s[4:5] offset:16 sc1
	s_nop 1
	v_lshlrev_b32_e32 v28, 16, v140
	v_and_b32_e32 v29, 0xffff0000, v140
	v_lshlrev_b32_e32 v30, 16, v141
	v_and_b32_e32 v31, 0xffff0000, v141
	v_pk_add_f32 v[28:29], v[32:33], v[28:29]
	v_lshlrev_b32_e32 v32, 16, v142
	v_and_b32_e32 v33, 0xffff0000, v142
	v_pk_add_f32 v[30:31], v[34:35], v[30:31]
	v_lshlrev_b32_e32 v34, 16, v143
	v_and_b32_e32 v35, 0xffff0000, v143
	v_pk_add_f32 v[24:25], v[24:25], v[32:33]
	v_add_u32_e32 v32, 0xa0000, v176
	v_pk_add_f32 v[26:27], v[26:27], v[34:35]
	global_store_dwordx4 v32, v[28:31], s[4:5] sc1
	global_store_dwordx4 v32, v[24:27], s[4:5] offset:16 sc1
	s_nop 1
	v_lshlrev_b32_e32 v24, 16, v136
	v_and_b32_e32 v25, 0xffff0000, v136
	v_lshlrev_b32_e32 v26, 16, v137
	v_and_b32_e32 v27, 0xffff0000, v137
	v_pk_add_f32 v[20:21], v[20:21], v[24:25]
	v_lshlrev_b32_e32 v24, 16, v138
	v_and_b32_e32 v25, 0xffff0000, v138
	v_pk_add_f32 v[22:23], v[22:23], v[26:27]
	v_lshlrev_b32_e32 v26, 16, v139
	v_and_b32_e32 v27, 0xffff0000, v139
	v_pk_add_f32 v[12:13], v[12:13], v[24:25]
	v_add_u32_e32 v24, 0xa0200, v176
	v_pk_add_f32 v[14:15], v[14:15], v[26:27]
	global_store_dwordx4 v24, v[20:23], s[4:5] sc1
	global_store_dwordx4 v24, v[12:15], s[4:5] offset:16 sc1
	s_nop 1
	v_lshlrev_b32_e32 v12, 16, v132
	v_and_b32_e32 v13, 0xffff0000, v132
	v_lshlrev_b32_e32 v14, 16, v133
	v_and_b32_e32 v15, 0xffff0000, v133
	v_pk_add_f32 v[12:13], v[16:17], v[12:13]
	v_lshlrev_b32_e32 v16, 16, v134
	v_and_b32_e32 v17, 0xffff0000, v134
	v_pk_add_f32 v[14:15], v[18:19], v[14:15]
	v_lshlrev_b32_e32 v18, 16, v135
	v_and_b32_e32 v19, 0xffff0000, v135
	v_pk_add_f32 v[8:9], v[8:9], v[16:17]
	v_add_u32_e32 v16, 0xb0000, v176
	v_pk_add_f32 v[10:11], v[10:11], v[18:19]
	global_store_dwordx4 v16, v[12:15], s[4:5] sc1
	global_store_dwordx4 v16, v[8:11], s[4:5] offset:16 sc1
	s_nop 1
	v_lshlrev_b32_e32 v8, 16, v128
	v_and_b32_e32 v9, 0xffff0000, v128
	v_lshlrev_b32_e32 v10, 16, v129
	v_and_b32_e32 v11, 0xffff0000, v129
	v_pk_add_f32 v[4:5], v[4:5], v[8:9]
	v_lshlrev_b32_e32 v8, 16, v130
	v_and_b32_e32 v9, 0xffff0000, v130
	v_pk_add_f32 v[6:7], v[6:7], v[10:11]
	v_lshlrev_b32_e32 v10, 16, v131
	v_and_b32_e32 v11, 0xffff0000, v131
	v_pk_add_f32 v[0:1], v[0:1], v[8:9]
	v_add_u32_e32 v8, 0xb0200, v176
	v_pk_add_f32 v[2:3], v[2:3], v[10:11]
	global_store_dwordx4 v8, v[4:7], s[4:5] sc1
	global_store_dwordx4 v8, v[0:3], s[4:5] offset:16 sc1
	s_cbranch_scc0 .LBB0_1381
	s_waitcnt vmcnt(0)
	s_cmpk_gt_u32 s33, 0xff
	s_cbranch_scc1 .LBB0_1392
	s_barrier
